# XCD-local barriers for seams P3-P7 (no wbl2/inv), placement check with fallback
# speedup vs baseline: 1.0134x; 1.0134x over previous
_Z8skel_fwd4Args:
	s_load_dwordx8 s[68:75], s[0:1], 0x80
	s_load_dword s3, s[0:1], 0xb0
	s_load_dwordx2 s[76:77], s[0:1], 0xa0
	s_load_dword s4, s[0:1], 0xa8
	v_mov_b32_e32 v3, 0
	v_and_b32_e32 v1, 0x3ff, v0
	s_add_u32 s6, s0, 0xb0
	v_readfirstlane_b32 s33, v1
	v_mbcnt_lo_u32_b32 v3, -1, v3
	s_addc_u32 s7, s1, 0
	s_andn2_b32 s33, s33, 63
	v_mbcnt_hi_u32_b32 v3, -1, v3
	v_add_u32_e32 v3, s33, v3
	s_waitcnt lgkmcnt(0)
	v_writelane_b32 v255, s4, 0
	v_mov_b32_e32 v2, 0
	s_nop 0
	v_cmp_eq_u32_e32 vcc, 0, v3
	s_and_saveexec_b64 s[4:5], vcc
	s_cbranch_execz .LBB0_3
	s_add_i32 s10, 0, 0x25fd0
	v_mov_b32_e32 v3, s10
	s_add_i32 s10, 0, 0x25fd4
	s_mov_b64 s[8:9], exec
	ds_write_b32 v3, v2
	v_mov_b32_e32 v3, s10
	ds_write_b32 v3, v2
	v_mbcnt_lo_u32_b32 v2, s8, 0
	v_mbcnt_hi_u32_b32 v2, s9, v2
	v_cmp_eq_u32_e32 vcc, 0, v2
	s_getreg_b32 s10, hwreg(HW_REG_XCC_ID, 0, 4)
	s_and_b64 s[12:13], exec, vcc
	s_mov_b64 exec, s[12:13]
	s_cbranch_execz .LBB0_3
	s_and_b32 s98, s10, 15
	s_add_i32 s98, s98, 1
	s_lshl_b32 s100, s2, 2
	s_add_i32 s100, s100, 0xe000
	v_mov_b32_e32 v4, s100
	v_mov_b32_e32 v5, s98
	global_atomic_add v4, v5, s[76:77]
	s_lshl_b32 s10, s10, 8
	s_and_b32 s10, s10, 0xf00
	s_add_u32 s10, s76, s10
	s_addc_u32 s11, s77, 0
	s_bcnt1_i32_b64 s8, s[8:9]
	v_mov_b32_e32 v2, 0x8000
	v_mov_b32_e32 v3, s8
	global_atomic_add v2, v3, s[10:11] offset:1024

.LBB0_126:
	s_mov_b32 s99, 0
	s_cmp_lg_u32 s3, 0x100
	s_cbranch_scc1 .Lflag_done
	v_mbcnt_lo_u32_b32 v0, -1, 0
	v_mbcnt_hi_u32_b32 v0, -1, v0
	v_lshlrev_b32_e32 v1, 4, v0
	v_add_u32_e32 v1, 0xe000, v1
	global_load_dwordx4 v[4:7], v1, s[76:77]
	v_and_b32_e32 v2, 1, v0
	s_waitcnt vmcnt(0)
	v_readlane_b32 s4, v4, 0
	v_readlane_b32 s5, v5, 0
	v_readlane_b32 s6, v6, 0
	v_readlane_b32 s7, v7, 0
	v_readlane_b32 s8, v4, 1
	v_readlane_b32 s9, v5, 1
	v_readlane_b32 s10, v6, 1
	v_readlane_b32 s11, v7, 1
	v_cmp_eq_u32_e32 vcc, 1, v2
	v_mov_b32_e32 v8, s4
	v_mov_b32_e32 v9, s8
	v_cndmask_b32_e32 v8, v8, v9, vcc
	v_mov_b32_e32 v10, s5
	v_mov_b32_e32 v9, s9
	v_cndmask_b32_e32 v10, v10, v9, vcc
	v_mov_b32_e32 v11, s6
	v_mov_b32_e32 v9, s10
	v_cndmask_b32_e32 v11, v11, v9, vcc
	v_mov_b32_e32 v12, s7
	v_mov_b32_e32 v9, s11
	v_cndmask_b32_e32 v12, v12, v9, vcc
	v_xor_b32_e32 v8, v4, v8
	v_xor_b32_e32 v10, v5, v10
	v_xor_b32_e32 v11, v6, v11
	v_xor_b32_e32 v12, v7, v12
	v_or3_b32 v8, v8, v10, v11
	v_or_b32_e32 v8, v8, v12
	v_min_u32_e32 v9, v4, v5
	v_min3_u32 v9, v9, v6, v7
	v_cmp_ne_u32_e32 vcc, 0, v8
	v_cmp_eq_u32_e64 s[4:5], 0, v9
	s_nop 3
	s_or_b64 s[4:5], vcc, s[4:5]
	s_cmp_lg_u64 s[4:5], 0
	s_cbranch_scc1 .Lflag_done
	s_mov_b32 s99, 1

.LBB0_641:
	s_cmp_eq_u32 s99, 0
	s_cbranch_scc1 .Lfull_3
	s_waitcnt vmcnt(0) lgkmcnt(0)
	s_barrier
	s_cmp_lg_u32 s33, 0
	s_cbranch_scc1 .Lls_join_3
	s_mov_b64 exec, 1
	s_add_i32 s98, 0, 0x25fd0
	v_mov_b32_e32 v0, s98
	ds_read_b32 v2, v0
	s_getreg_b32 s98, hwreg(HW_REG_XCC_ID, 0, 4)
	s_and_b32 s98, s98, 15
	s_lshl_b32 s98, s98, 8
	s_add_u32 s100, s76, s98
	s_addc_u32 s101, s77, 0
	v_mov_b32_e32 v0, 0xc000
	v_mov_b32_e32 v1, 1
	global_atomic_add v0, v1, s[100:101]
	s_waitcnt lgkmcnt(0)
	v_mul_lo_u32 v2, v2, 1
	s_mov_b32 s98, 0
.Lls_spin_3:
	global_load_dword v3, v0, s[100:101] sc1
	s_waitcnt vmcnt(0)
	v_cmp_ge_u32_e32 vcc, v3, v2
	s_cbranch_vccnz .Lls_spun_3
	s_sleep 1
	s_add_i32 s98, s98, 1
	s_cmp_lt_u32 s98, 0x4000
	s_cbranch_scc1 .Lls_spin_3
.Lls_spun_3:
	s_mov_b64 exec, -1
.Lls_join_3:
	s_barrier
	s_branch .LBB0_694

.LBB0_743:
	s_cmp_eq_u32 s99, 0
	s_cbranch_scc1 .Lfull_4
	s_waitcnt vmcnt(0) lgkmcnt(0)
	s_barrier
	s_cmp_lg_u32 s33, 0
	s_cbranch_scc1 .Lls_join_4
	s_mov_b64 exec, 1
	s_add_i32 s98, 0, 0x25fd0
	v_mov_b32_e32 v0, s98
	ds_read_b32 v2, v0
	s_getreg_b32 s98, hwreg(HW_REG_XCC_ID, 0, 4)
	s_and_b32 s98, s98, 15
	s_lshl_b32 s98, s98, 8
	s_add_u32 s100, s76, s98
	s_addc_u32 s101, s77, 0
	v_mov_b32_e32 v0, 0xc000
	v_mov_b32_e32 v1, 1
	global_atomic_add v0, v1, s[100:101]
	s_waitcnt lgkmcnt(0)
	v_mul_lo_u32 v2, v2, 2
	s_mov_b32 s98, 0

.LBB0_819:
	s_cmp_eq_u32 s99, 0
	s_cbranch_scc1 .Lfull_5
	s_waitcnt vmcnt(0) lgkmcnt(0)
	s_barrier
	s_cmp_lg_u32 s33, 0
	s_cbranch_scc1 .Lls_join_5
	s_mov_b64 exec, 1
	s_add_i32 s98, 0, 0x25fd0
	v_mov_b32_e32 v0, s98
	ds_read_b32 v2, v0
	s_getreg_b32 s98, hwreg(HW_REG_XCC_ID, 0, 4)
	s_and_b32 s98, s98, 15
	s_lshl_b32 s98, s98, 8
	s_add_u32 s100, s76, s98
	s_addc_u32 s101, s77, 0
	v_mov_b32_e32 v0, 0xc000
	v_mov_b32_e32 v1, 1
	global_atomic_add v0, v1, s[100:101]
	s_waitcnt lgkmcnt(0)
	v_mul_lo_u32 v2, v2, 3
	s_mov_b32 s98, 0

.LBB0_925:
	s_cmp_eq_u32 s99, 0
	s_cbranch_scc1 .Lfull_6
	s_waitcnt vmcnt(0) lgkmcnt(0)
	s_barrier
	s_cmp_lg_u32 s33, 0
	s_cbranch_scc1 .Lls_join_6
	s_mov_b64 exec, 1
	s_add_i32 s98, 0, 0x25fd0
	v_mov_b32_e32 v0, s98
	ds_read_b32 v2, v0
	s_getreg_b32 s98, hwreg(HW_REG_XCC_ID, 0, 4)
	s_and_b32 s98, s98, 15
	s_lshl_b32 s98, s98, 8
	s_add_u32 s100, s76, s98
	s_addc_u32 s101, s77, 0
	v_mov_b32_e32 v0, 0xc000
	v_mov_b32_e32 v1, 1
	global_atomic_add v0, v1, s[100:101]
	s_waitcnt lgkmcnt(0)
	v_mul_lo_u32 v2, v2, 4
	s_mov_b32 s98, 0

	.amdhsa_kernel _Z8skel_fwd4Args
		.amdhsa_group_segment_fixed_size 0
		.amdhsa_private_segment_fixed_size 0
		.amdhsa_kernarg_size 432
		.amdhsa_user_sgpr_count 2
		.amdhsa_user_sgpr_dispatch_ptr 0
		.amdhsa_user_sgpr_queue_ptr 0
		.amdhsa_user_sgpr_kernarg_segment_ptr 1
		.amdhsa_user_sgpr_dispatch_id 0
		.amdhsa_user_sgpr_kernarg_preload_length 0
		.amdhsa_user_sgpr_kernarg_preload_offset 0
		.amdhsa_user_sgpr_private_segment_size 0
		.amdhsa_uses_dynamic_stack 0
		.amdhsa_enable_private_segment 0
		.amdhsa_system_sgpr_workgroup_id_x 1
		.amdhsa_system_sgpr_workgroup_id_y 0
		.amdhsa_system_sgpr_workgroup_id_z 0
		.amdhsa_system_sgpr_workgroup_info 0
		.amdhsa_system_vgpr_workitem_id 2
		.amdhsa_next_free_vgpr 256
		.amdhsa_next_free_sgpr 102
		.amdhsa_accum_offset 256
		.amdhsa_reserve_vcc 1
		.amdhsa_float_round_mode_32 0
		.amdhsa_float_round_mode_16_64 0
		.amdhsa_float_denorm_mode_32 3
		.amdhsa_float_denorm_mode_16_64 3
		.amdhsa_dx10_clamp 1
		.amdhsa_ieee_mode 1
		.amdhsa_fp16_overflow 0
		.amdhsa_tg_split 0
		.amdhsa_exception_fp_ieee_invalid_op 0
		.amdhsa_exception_fp_denorm_src 0
		.amdhsa_exception_fp_ieee_div_zero 0
		.amdhsa_exception_fp_ieee_overflow 0
		.amdhsa_exception_fp_ieee_underflow 0
		.amdhsa_exception_fp_ieee_inexact 0
		.amdhsa_exception_int_div_zero 0
	.end_amdhsa_kernel

amdhsa.kernels:
  - .agpr_count:     0
    .args:
      - .offset:         0
        .size:           176
        .value_kind:     by_value
      - .offset:         176
        .size:           4
        .value_kind:     hidden_block_count_x
      - .offset:         180
        .size:           4
        .value_kind:     hidden_block_count_y
      - .offset:         184
        .size:           4
        .value_kind:     hidden_block_count_z
      - .offset:         188
        .size:           2
        .value_kind:     hidden_group_size_x
      - .offset:         190
        .size:           2
        .value_kind:     hidden_group_size_y
      - .offset:         192
        .size:           2
        .value_kind:     hidden_group_size_z
      - .offset:         194
        .size:           2
        .value_kind:     hidden_remainder_x
      - .offset:         196
        .size:           2
        .value_kind:     hidden_remainder_y
      - .offset:         198
        .size:           2
        .value_kind:     hidden_remainder_z
      - .offset:         216
        .size:           8
        .value_kind:     hidden_global_offset_x
      - .offset:         224
        .size:           8
        .value_kind:     hidden_global_offset_y
      - .offset:         232
        .size:           8
        .value_kind:     hidden_global_offset_z
      - .offset:         240
        .size:           2
        .value_kind:     hidden_grid_dims
      - .offset:         264
        .size:           8
        .value_kind:     hidden_multigrid_sync_arg
      - .offset:         296
        .size:           4
        .value_kind:     hidden_dynamic_lds_size
    .group_segment_fixed_size: 0
    .kernarg_segment_align: 8
    .kernarg_segment_size: 432
    .language:       OpenCL C
    .language_version:
      - 2
      - 0
    .max_flat_workgroup_size: 512
    .name:           _Z8skel_fwd4Args
    .private_segment_fixed_size: 0
    .sgpr_count:     108
    .sgpr_spill_count: 14
    .symbol:         _Z8skel_fwd4Args.kd
    .uniform_work_group_size: 1
    .uses_dynamic_stack: false
    .vgpr_count:     256
    .vgpr_spill_count: 0
    .wavefront_size: 64
